# v84 + LDS read pipelining in the MoBA k-mean gating and the NSA compressed-branch QK fragment reads (no barrier removals)
# baseline (speedup 1.0000x reference)
.LBB0_895:
	s_cmp_lg_u32 s55, 0
	v_writelane_b32 v240, s55, 20
	s_cbranch_scc0 .LBB0_939
	v_lshl_add_u32 v128, s93, 8, v154
	s_ashr_i32 s1, s0, 31
	v_ashrrev_i32_e32 v129, 31, v128
	s_lshl_b64 s[4:5], s[0:1], 11
	v_lshl_add_u64 v[0:1], s[4:5], 0, v[128:129]
	v_lshlrev_b64 v[0:1], 7, v[0:1]
	v_lshl_add_u64 v[0:1], v[134:135], 0, v[0:1]
	global_load_dwordx4 v[80:83], v[0:1], off
	global_load_dwordx4 v[84:87], v[0:1], off offset:32
	global_load_dwordx4 v[88:91], v[0:1], off offset:64
	global_load_dwordx4 v[92:95], v[0:1], off offset:96
	s_cmp_gt_i32 s93, 3
	s_mov_b64 s[14:15], -1
	s_cbranch_scc0 .LBB0_904
	v_lshl_add_u64 v[0:1], v[136:137], 0, s[4:5]
	global_load_dword v17, v[0:1], off
	s_waitcnt vmcnt(4)
	v_lshlrev_b32_e32 v19, 16, v80
	v_and_b32_e32 v20, 0xffff0000, v80
	v_lshlrev_b32_e32 v21, 16, v81
	v_and_b32_e32 v22, 0xffff0000, v81
	v_lshlrev_b32_e32 v23, 16, v82
	v_and_b32_e32 v24, 0xffff0000, v82
	v_lshlrev_b32_e32 v25, 16, v83
	v_and_b32_e32 v26, 0xffff0000, v83
	s_waitcnt vmcnt(3)
	v_lshlrev_b32_e32 v27, 16, v84
	v_and_b32_e32 v28, 0xffff0000, v84
	v_lshlrev_b32_e32 v29, 16, v85
	v_and_b32_e32 v30, 0xffff0000, v85
	v_lshlrev_b32_e32 v31, 16, v86
	v_and_b32_e32 v32, 0xffff0000, v86
	v_lshlrev_b32_e32 v33, 16, v87
	v_and_b32_e32 v34, 0xffff0000, v87
	s_waitcnt vmcnt(2)
	v_lshlrev_b32_e32 v13, 16, v88
	v_and_b32_e32 v14, 0xffff0000, v88
	v_lshlrev_b32_e32 v15, 16, v89
	v_and_b32_e32 v16, 0xffff0000, v89
	v_lshlrev_b32_e32 v10, 16, v90
	v_and_b32_e32 v11, 0xffff0000, v90
	v_lshlrev_b32_e32 v8, 16, v91
	v_and_b32_e32 v9, 0xffff0000, v91
	s_waitcnt vmcnt(1)
	v_lshlrev_b32_e32 v4, 16, v92
	v_and_b32_e32 v5, 0xffff0000, v92
	v_lshlrev_b32_e32 v6, 16, v93
	v_and_b32_e32 v7, 0xffff0000, v93
	v_lshlrev_b32_e32 v0, 16, v94
	v_and_b32_e32 v1, 0xffff0000, v94
	v_lshlrev_b32_e32 v2, 16, v95
	v_and_b32_e32 v3, 0xffff0000, v95
	s_cmp_lg_u32 s93, 4
	v_mov_b32_e32 v12, 0
	s_cselect_b64 s[4:5], -1, 0
	s_cmp_eq_u32 s93, 4
	s_waitcnt vmcnt(0)
	ds_write_b32 v133, v17
	s_waitcnt lgkmcnt(0)
	s_barrier
	ds_read_b128 v[116:119], v155
	ds_read_b128 v[120:123], v155 offset:16
	ds_read_b128 v[124:127], v155 offset:64
	ds_read_b128 v[216:219], v155 offset:80
	ds_read_b128 v[220:223], v155 offset:128
	ds_read_b128 v[224:227], v155 offset:144
	ds_read_b128 v[228:231], v155 offset:192
	ds_read_b128 v[232:235], v155 offset:208
	ds_read_b128 v[236:239], v155 offset:256
	ds_read_b128 v[244:247], v155 offset:272
	ds_read_b128 v[248:251], v155 offset:320
	ds_read_b128 v[252:255], v155 offset:336
	ds_read_b128 v[48:51], v155 offset:384
	ds_read_b128 v[52:55], v155 offset:400
	ds_read_b128 v[56:59], v155 offset:448
	ds_read_b128 v[60:63], v155 offset:464
	ds_read_b128 v[64:67], v155 offset:512
	ds_read_b128 v[68:71], v155 offset:528
	ds_read_b128 v[72:75], v155 offset:576
	ds_read_b128 v[76:79], v155 offset:592
	ds_read_b128 v[96:99], v155 offset:640
	ds_read_b128 v[100:103], v155 offset:656
	s_waitcnt lgkmcnt(15)
	v_fma_f32 v18, v116, v19, 0
	v_fmac_f32_e32 v18, v117, v20
	v_fmac_f32_e32 v18, v118, v21
	v_fmac_f32_e32 v18, v119, v22
	v_fmac_f32_e32 v18, v120, v23
	v_fmac_f32_e32 v18, v121, v24
	v_fmac_f32_e32 v18, v122, v25
	v_fmac_f32_e32 v18, v123, v26
	ds_read_b128 v[116:119], v155 offset:704
	v_fmac_f32_e32 v18, v124, v27
	v_fmac_f32_e32 v18, v125, v28
	v_fmac_f32_e32 v18, v126, v29
	v_fmac_f32_e32 v18, v127, v30
	ds_read_b128 v[120:123], v155 offset:720
	s_waitcnt lgkmcnt(7)
	v_fma_f32 v39, v64, v19, 0
	v_fmac_f32_e32 v39, v65, v20
	v_fmac_f32_e32 v39, v66, v21
	v_fmac_f32_e32 v39, v67, v22
	ds_read_b128 v[124:127], v155 offset:768
	s_waitcnt lgkmcnt(7)
	v_fmac_f32_e32 v39, v68, v23
	v_fmac_f32_e32 v39, v69, v24
	v_fmac_f32_e32 v39, v70, v25
	v_fmac_f32_e32 v39, v71, v26
	ds_read_b128 v[64:67], v155 offset:784
	s_waitcnt lgkmcnt(7)
	v_fmac_f32_e32 v39, v72, v27
	v_fmac_f32_e32 v39, v73, v28
	v_fmac_f32_e32 v39, v74, v29
	v_fmac_f32_e32 v39, v75, v30
	ds_read_b128 v[68:71], v155 offset:832
	s_waitcnt lgkmcnt(7)
	v_fmac_f32_e32 v39, v76, v31
	v_fmac_f32_e32 v39, v77, v32
	v_fmac_f32_e32 v39, v78, v33
	v_fmac_f32_e32 v39, v79, v34
	ds_read_b128 v[72:75], v155 offset:848
	s_waitcnt lgkmcnt(7)
	v_fmac_f32_e32 v39, v96, v13
	v_fmac_f32_e32 v39, v97, v14
	v_fmac_f32_e32 v39, v98, v15
	v_fmac_f32_e32 v39, v99, v16
	ds_read_b128 v[76:79], v155 offset:896
	s_waitcnt lgkmcnt(7)
	v_fmac_f32_e32 v39, v100, v10
	v_fmac_f32_e32 v39, v101, v11
	v_fmac_f32_e32 v39, v102, v8
	v_fmac_f32_e32 v39, v103, v9
	ds_read_b128 v[96:99], v155 offset:912
	s_waitcnt lgkmcnt(7)
	v_fmac_f32_e32 v39, v116, v4
	v_fmac_f32_e32 v39, v117, v5
	v_fmac_f32_e32 v39, v118, v6
	v_fmac_f32_e32 v39, v119, v7
	s_waitcnt lgkmcnt(6)
	v_fmac_f32_e32 v39, v120, v0
	v_fmac_f32_e32 v39, v121, v1
	ds_read_b128 v[116:119], v155 offset:960
	v_fmac_f32_e32 v18, v216, v31
	v_fmac_f32_e32 v39, v122, v2
	v_fmac_f32_e32 v18, v217, v32
	v_fmac_f32_e32 v39, v123, v3
	ds_read_b128 v[120:123], v155 offset:976
	v_fma_f32 v17, v236, v19, 0
	v_fmac_f32_e32 v18, v218, v33
	s_waitcnt lgkmcnt(7)
	v_fma_f32 v42, v124, v19, 0
	v_fmac_f32_e32 v17, v237, v20
	v_fmac_f32_e32 v18, v219, v34
	v_fmac_f32_e32 v42, v125, v20
	v_fmac_f32_e32 v17, v238, v21
	v_fmac_f32_e32 v18, v220, v13
	v_fmac_f32_e32 v42, v126, v21
	v_fmac_f32_e32 v17, v239, v22
	v_fmac_f32_e32 v18, v221, v14
	v_fmac_f32_e32 v42, v127, v22
	v_fmac_f32_e32 v17, v244, v23
	s_waitcnt lgkmcnt(6)
	v_fmac_f32_e32 v42, v64, v23
	v_fmac_f32_e32 v17, v245, v24
	v_fmac_f32_e32 v42, v65, v24
	v_fmac_f32_e32 v17, v246, v25
	v_fmac_f32_e32 v42, v66, v25
	v_fmac_f32_e32 v17, v247, v26
	v_fmac_f32_e32 v42, v67, v26
	v_fmac_f32_e32 v17, v248, v27
	s_waitcnt lgkmcnt(5)
	v_fmac_f32_e32 v42, v68, v27
	v_fmac_f32_e32 v17, v249, v28
	v_fmac_f32_e32 v42, v69, v28
	v_fmac_f32_e32 v17, v250, v29
	v_fmac_f32_e32 v42, v70, v29
	v_fmac_f32_e32 v17, v251, v30
	v_fmac_f32_e32 v42, v71, v30
	v_fmac_f32_e32 v17, v252, v31
	s_waitcnt lgkmcnt(4)
	v_fmac_f32_e32 v42, v72, v31
	v_fmac_f32_e32 v17, v253, v32
	v_fmac_f32_e32 v42, v73, v32
	v_fmac_f32_e32 v17, v254, v33
	v_fmac_f32_e32 v42, v74, v33
	v_fmac_f32_e32 v17, v255, v34
	v_fmac_f32_e32 v42, v75, v34
	v_fmac_f32_e32 v17, v48, v13
	s_waitcnt lgkmcnt(3)
	v_fmac_f32_e32 v42, v76, v13
	v_fmac_f32_e32 v17, v49, v14
	v_fmac_f32_e32 v42, v77, v14
	v_fmac_f32_e32 v18, v222, v15
	v_fmac_f32_e32 v17, v50, v15
	v_fmac_f32_e32 v42, v78, v15
	v_fmac_f32_e32 v18, v223, v16
	v_fmac_f32_e32 v17, v51, v16
	v_fmac_f32_e32 v42, v79, v16
	v_fmac_f32_e32 v18, v224, v10
	v_fmac_f32_e32 v17, v52, v10
	s_waitcnt lgkmcnt(2)
	v_fmac_f32_e32 v42, v96, v10
	v_fmac_f32_e32 v18, v225, v11
	v_fmac_f32_e32 v17, v53, v11
	v_fmac_f32_e32 v42, v97, v11
	v_fmac_f32_e32 v18, v226, v8
	v_fmac_f32_e32 v17, v54, v8
	v_fmac_f32_e32 v42, v98, v8
	v_fmac_f32_e32 v18, v227, v9
	v_fmac_f32_e32 v17, v55, v9
	v_fmac_f32_e32 v42, v99, v9
	v_fmac_f32_e32 v18, v228, v4
	v_fmac_f32_e32 v17, v56, v4
	s_waitcnt lgkmcnt(1)
	v_fmac_f32_e32 v42, v116, v4
	v_fmac_f32_e32 v18, v229, v5
	v_fmac_f32_e32 v17, v57, v5
	v_fmac_f32_e32 v42, v117, v5
	v_fmac_f32_e32 v18, v230, v6
	v_fmac_f32_e32 v17, v58, v6
	v_fmac_f32_e32 v42, v118, v6
	v_fmac_f32_e32 v18, v231, v7
	v_fmac_f32_e32 v17, v59, v7
	v_fmac_f32_e32 v42, v119, v7
	v_fmac_f32_e32 v18, v232, v0
	v_fmac_f32_e32 v17, v60, v0
	s_waitcnt lgkmcnt(0)
	v_fmac_f32_e32 v42, v120, v0
	v_fmac_f32_e32 v18, v233, v1
	v_fmac_f32_e32 v17, v61, v1
	v_fmac_f32_e32 v42, v121, v1
	v_fmac_f32_e32 v18, v234, v2
	v_fmac_f32_e32 v17, v62, v2
	v_fmac_f32_e32 v42, v122, v2
	v_fmac_f32_e32 v18, v235, v3
	v_fmac_f32_e32 v17, v63, v3
	v_fmac_f32_e32 v42, v123, v3
	v_mov_b32_e32 v35, v18
	v_mov_b32_e32 v36, v18
	v_mov_b32_e32 v37, v17
	v_mov_b32_e32 v38, v17
	v_mov_b32_e32 v40, v39
	v_mov_b32_e32 v41, v39
	v_mov_b32_e32 v43, v42
	v_mov_b32_e32 v44, v42
	v_permlane32_swap_b32_e32 v35, v36
	v_permlane32_swap_b32_e32 v37, v38
	v_permlane32_swap_b32_e32 v40, v41
	v_permlane32_swap_b32_e32 v43, v44
	v_mov_b32_e32 v45, 0
	s_cbranch_scc1 .LBB0_899
	ds_read_b128 v[116:119], v155 offset:1024
	ds_read_b128 v[120:123], v155 offset:1040
	ds_read_b128 v[124:127], v155 offset:1088
	ds_read_b128 v[216:219], v155 offset:1104
	ds_read_b128 v[220:223], v155 offset:1152
	ds_read_b128 v[224:227], v155 offset:1168
	ds_read_b128 v[228:231], v155 offset:1216
	ds_read_b128 v[232:235], v155 offset:1232
	s_waitcnt lgkmcnt(7)
	v_fma_f32 v45, v116, v19, 0
	v_fmac_f32_e32 v45, v117, v20
	v_fmac_f32_e32 v45, v118, v21
	v_fmac_f32_e32 v45, v119, v22
	s_waitcnt lgkmcnt(6)
	v_fmac_f32_e32 v45, v120, v23
	v_fmac_f32_e32 v45, v121, v24
	v_fmac_f32_e32 v45, v122, v25
	v_fmac_f32_e32 v45, v123, v26
	s_waitcnt lgkmcnt(5)
	v_fmac_f32_e32 v45, v124, v27
	v_fmac_f32_e32 v45, v125, v28
	v_fmac_f32_e32 v45, v126, v29
	v_fmac_f32_e32 v45, v127, v30
	s_waitcnt lgkmcnt(4)
	v_fmac_f32_e32 v45, v216, v31
	v_fmac_f32_e32 v45, v217, v32
	v_fmac_f32_e32 v45, v218, v33
	v_fmac_f32_e32 v45, v219, v34
	s_waitcnt lgkmcnt(3)
	v_fmac_f32_e32 v45, v220, v13
	v_fmac_f32_e32 v45, v221, v14
	v_fmac_f32_e32 v45, v222, v15
	v_fmac_f32_e32 v45, v223, v16
	s_waitcnt lgkmcnt(2)
	v_pk_mul_f32 v[46:47], v[224:225], v[10:11]
	s_waitcnt lgkmcnt(1)
	v_pk_mul_f32 v[50:51], v[228:229], v[4:5]
	v_add_f32_e32 v45, v45, v46
	v_add_f32_e32 v45, v45, v47
	v_pk_mul_f32 v[46:47], v[226:227], v[8:9]
	s_nop 0
	v_add_f32_e32 v45, v45, v46
	v_add_f32_e32 v45, v45, v47
	v_add_f32_e32 v45, v45, v50
	v_add_f32_e32 v45, v45, v51
	v_pk_mul_f32 v[50:51], v[230:231], v[6:7]
	s_waitcnt lgkmcnt(0)
	v_pk_mul_f32 v[46:47], v[232:233], v[0:1]
	v_add_f32_e32 v45, v45, v50
	v_add_f32_e32 v45, v45, v51
	v_add_f32_e32 v45, v45, v46
	v_add_f32_e32 v45, v45, v47
	v_pk_mul_f32 v[46:47], v[234:235], v[2:3]
	s_nop 0
	v_add_f32_e32 v45, v45, v46
	v_add_f32_e32 v45, v45, v47
	v_mov_b32_e32 v46, v45
	v_mov_b32_e32 v47, v45
	s_nop 1
	v_permlane32_swap_b32_e32 v46, v47
	v_cndmask_b32_e64 v46, v46, v47, s[6:7]
	v_add_f32_e32 v45, v45, v46
.LBB0_899:
	s_cmp_gt_u32 s93, 5
	s_cselect_b64 s[24:25], -1, 0
	s_cmp_lt_u32 s93, 6
	s_cbranch_scc1 .LBB0_901
	ds_read_b128 v[116:119], v155 offset:1280
	ds_read_b128 v[120:123], v155 offset:1296
	ds_read_b128 v[124:127], v155 offset:1344
	ds_read_b128 v[216:219], v155 offset:1360
	ds_read_b128 v[220:223], v155 offset:1408
	ds_read_b128 v[224:227], v155 offset:1424
	ds_read_b128 v[228:231], v155 offset:1472
	ds_read_b128 v[232:235], v155 offset:1488
	s_waitcnt lgkmcnt(7)
	v_fma_f32 v12, v116, v19, 0
	v_fmac_f32_e32 v12, v117, v20
	v_fmac_f32_e32 v12, v118, v21
	v_fmac_f32_e32 v12, v119, v22
	s_waitcnt lgkmcnt(6)
	v_fmac_f32_e32 v12, v120, v23
	v_fmac_f32_e32 v12, v121, v24
	v_fmac_f32_e32 v12, v122, v25
	v_fmac_f32_e32 v12, v123, v26
	s_waitcnt lgkmcnt(5)
	v_fmac_f32_e32 v12, v124, v27
	v_fmac_f32_e32 v12, v125, v28
	v_fmac_f32_e32 v12, v126, v29
	v_fmac_f32_e32 v12, v127, v30
	s_waitcnt lgkmcnt(4)
	v_fmac_f32_e32 v12, v216, v31
	v_fmac_f32_e32 v12, v217, v32
	v_fmac_f32_e32 v12, v218, v33
	v_fmac_f32_e32 v12, v219, v34
	s_waitcnt lgkmcnt(3)
	v_fmac_f32_e32 v12, v220, v13
	v_fmac_f32_e32 v12, v221, v14
	v_fmac_f32_e32 v12, v222, v15
	v_fmac_f32_e32 v12, v223, v16
	s_waitcnt lgkmcnt(2)
	v_pk_mul_f32 v[46:47], v[224:225], v[10:11]
	s_waitcnt lgkmcnt(1)
	v_pk_mul_f32 v[50:51], v[228:229], v[4:5]
	v_add_f32_e32 v12, v12, v46
	v_add_f32_e32 v12, v12, v47
	v_pk_mul_f32 v[46:47], v[226:227], v[8:9]
	s_nop 0
	v_add_f32_e32 v12, v12, v46
	v_add_f32_e32 v12, v12, v47
	v_add_f32_e32 v12, v12, v50
	v_add_f32_e32 v12, v12, v51
	v_pk_mul_f32 v[50:51], v[230:231], v[6:7]
	s_waitcnt lgkmcnt(0)
	v_pk_mul_f32 v[46:47], v[232:233], v[0:1]
	v_add_f32_e32 v12, v12, v50
	v_add_f32_e32 v12, v12, v51
	v_add_f32_e32 v12, v12, v46
	v_add_f32_e32 v12, v12, v47
	v_pk_mul_f32 v[46:47], v[234:235], v[2:3]
	s_nop 0
	v_add_f32_e32 v12, v12, v46
	v_add_f32_e32 v12, v12, v47
	v_mov_b32_e32 v46, v12
	v_mov_b32_e32 v47, v12
	s_nop 1
	v_permlane32_swap_b32_e32 v46, v47
	v_cndmask_b32_e64 v46, v46, v47, s[6:7]
	v_add_f32_e32 v12, v12, v46
.LBB0_901:
	s_cmp_gt_u32 s93, 6
	s_cselect_b64 s[26:27], -1, 0
	s_cmp_lt_u32 s93, 7
	v_mov_b32_e32 v46, 0
	s_cbranch_scc1 .LBB0_903
	ds_read_b128 v[116:119], v155 offset:1536
	ds_read_b128 v[120:123], v155 offset:1552
	ds_read_b128 v[124:127], v155 offset:1600
	ds_read_b128 v[216:219], v155 offset:1616
	ds_read_b128 v[220:223], v155 offset:1664
	ds_read_b128 v[224:227], v155 offset:1680
	ds_read_b128 v[228:231], v155 offset:1728
	ds_read_b128 v[232:235], v155 offset:1744
	s_waitcnt lgkmcnt(7)
	v_fma_f32 v19, v116, v19, 0
	v_fmac_f32_e32 v19, v117, v20
	v_fmac_f32_e32 v19, v118, v21
	v_fmac_f32_e32 v19, v119, v22
	s_waitcnt lgkmcnt(6)
	v_fmac_f32_e32 v19, v120, v23
	v_fmac_f32_e32 v19, v121, v24
	v_fmac_f32_e32 v19, v122, v25
	v_fmac_f32_e32 v19, v123, v26
	s_waitcnt lgkmcnt(5)
	v_fmac_f32_e32 v19, v124, v27
	v_fmac_f32_e32 v19, v125, v28
	v_fmac_f32_e32 v19, v126, v29
	v_fmac_f32_e32 v19, v127, v30
	s_waitcnt lgkmcnt(4)
	v_fmac_f32_e32 v19, v216, v31
	v_fmac_f32_e32 v19, v217, v32
	v_fmac_f32_e32 v19, v218, v33
	v_fmac_f32_e32 v19, v219, v34
	s_waitcnt lgkmcnt(3)
	v_fmac_f32_e32 v19, v220, v13
	v_fmac_f32_e32 v19, v221, v14
	v_fmac_f32_e32 v19, v222, v15
	v_fmac_f32_e32 v19, v223, v16
	s_waitcnt lgkmcnt(2)
	v_pk_mul_f32 v[10:11], v[224:225], v[10:11]
	v_pk_mul_f32 v[8:9], v[226:227], v[8:9]
	v_add_f32_e32 v10, v19, v10
	v_add_f32_e32 v10, v10, v11
	v_add_f32_e32 v8, v10, v8
	v_add_f32_e32 v13, v8, v9
	s_waitcnt lgkmcnt(1)
	v_pk_mul_f32 v[4:5], v[228:229], v[4:5]
	s_waitcnt lgkmcnt(0)
	v_pk_mul_f32 v[0:1], v[232:233], v[0:1]
	v_add_f32_e32 v4, v13, v4
	v_add_f32_e32 v13, v4, v5
	v_pk_mul_f32 v[4:5], v[230:231], v[6:7]
	s_nop 0
	v_add_f32_e32 v4, v13, v4
	v_add_f32_e32 v4, v4, v5
	v_add_f32_e32 v0, v4, v0
	v_add_f32_e32 v4, v0, v1
	v_pk_mul_f32 v[0:1], v[234:235], v[2:3]
	s_nop 0
	v_add_f32_e32 v0, v4, v0
	v_add_f32_e32 v0, v0, v1
	v_mov_b32_e32 v1, v0
	v_mov_b32_e32 v2, v0
	s_nop 1
	v_permlane32_swap_b32_e32 v1, v2
	v_cndmask_b32_e64 v1, v1, v2, s[6:7]
	v_add_f32_e32 v46, v0, v1
